# pool staging: five global->LDS row pieces per thread requested together; P1 rotary table rows requested two row blocks ahead
# speedup vs baseline: 1.0049x; 1.0025x over previous
.Lp1_qkv:
	s_add_i32 s46, s10, -1
	s_mul_i32 s47, s46, 0x5556
	s_lshr_b32 s47, s47, 16
	s_mul_i32 s9, s47, 3
	s_sub_i32 s46, s46, s9
	s_lshl_b32 s46, s46, 2
	s_lshr_b32 s9, s8, 1
	s_add_i32 s46, s46, s9
	s_mul_i32 s46, s46, 0x600000
	s_mul_i32 s9, s47, 0x4800000
	s_add_i32 s46, s46, s9
	s_and_b32 s9, s8, 1
	s_lshl_b32 s9, s9, 6
	s_add_i32 s46, s46, s9
	s_add_u32 s20, s86, 0x9800000
	s_addc_u32 s21, s87, 0
	v_lshlrev_b32_e32 v155, 7, v154
	v_lshl_add_u32 v155, v153, 4, v155
	v_add_u32_e32 v155, s46, v155
	v_add_u32_e32 v156, 0xc00000, v155
	s_cmp_eq_u32 s47, 0
	s_cselect_b32 s9, 0x3e38aa3b, 1.0
	v_mov_b32_e32 v162, s9
	v_mov_b32_e32 v163, s9
	s_and_b32 s9, s8, 1
	s_cmp_lt_u32 s47, 2
	s_cselect_b32 s11, 1, 0
	s_andn2_b32 s11, s11, s9
	s_cmp_eq_u32 s11, 0
	s_cbranch_scc1 .Lp1_norope
	v_cmp_eq_u32_e32 vcc, 0, v153
	s_nop 1
	v_cndmask_b32_e64 v160, 1.0, -1.0, vcc
	v_mov_b32_e32 v161, v160
	v_and_b32_e32 v158, 1, v153
	v_cmp_eq_u32_e64 s[46:47], 1, v158
	v_cmp_gt_u32_e64 s[52:53], 2, v153
	s_movk_i32 s9, 0x3fff
	s_cmp_lt_u32 s81, 64
	s_cselect_b32 s9, 0x7ff, s9
	v_and_b32_e32 v157, s9, v154
	v_lshlrev_b32_e32 v157, 6, v157
	v_mov_b32_e32 v158, v157
	s_mov_b64 s[8:9], exec
	s_mov_b64 exec, s[52:53]
	global_load_dwordx4 v[164:167], v158, s[14:15] offset:0
	global_load_dwordx4 v[168:171], v158, s[14:15] offset:16
	global_load_dwordx4 v[192:195], v158, s[14:15] offset:32
	global_load_dwordx4 v[196:199], v158, s[14:15] offset:48
	s_mov_b64 exec, s[8:9]
	v_add_u32_e32 v158, 0x400, v157
	s_mov_b64 s[8:9], exec
	s_mov_b64 exec, s[52:53]
	global_load_dwordx4 v[200:203], v158, s[14:15] offset:0
	global_load_dwordx4 v[204:207], v158, s[14:15] offset:16
	global_load_dwordx4 v[208:211], v158, s[14:15] offset:32
	global_load_dwordx4 v[232:235], v158, s[14:15] offset:48
	s_mov_b64 exec, s[8:9]
	v_pk_mul_f32 v[124:125], v[124:125], v[248:249] op_sel_hi:[1,0]
	v_pk_mul_f32 v[126:127], v[126:127], v[248:249] op_sel_hi:[1,0]
	v_pk_mul_f32 v[120:121], v[120:121], v[248:249] op_sel_hi:[1,0]
	v_pk_mul_f32 v[122:123], v[122:123], v[248:249] op_sel_hi:[1,0]
	v_mov_b32_e32 v216, v124
	v_mov_b32_e32 v217, v124
	v_mov_b32_e32 v218, v125
	v_mov_b32_e32 v219, v125
	v_mov_b32_e32 v220, v126
	v_mov_b32_e32 v221, v126
	v_mov_b32_e32 v222, v127
	v_mov_b32_e32 v223, v127
	v_mov_b32_e32 v224, v120
	v_mov_b32_e32 v225, v120
	v_mov_b32_e32 v226, v121
	v_mov_b32_e32 v227, v121
	v_mov_b32_e32 v228, v122
	v_mov_b32_e32 v229, v122
	v_mov_b32_e32 v230, v123
	v_mov_b32_e32 v231, v123
	v_permlane16_swap_b32_e32 v216, v217
	v_permlane16_swap_b32_e32 v218, v219
	v_permlane16_swap_b32_e32 v220, v221
	v_permlane16_swap_b32_e32 v222, v223
	v_permlane16_swap_b32_e32 v224, v225
	v_permlane16_swap_b32_e32 v226, v227
	v_permlane16_swap_b32_e32 v228, v229
	v_permlane16_swap_b32_e32 v230, v231
	v_cndmask_b32_e64 v236, v217, v216, s[46:47]
	v_cndmask_b32_e64 v237, v219, v218, s[46:47]
	v_cndmask_b32_e64 v238, v221, v220, s[46:47]
	v_cndmask_b32_e64 v239, v223, v222, s[46:47]
	v_cndmask_b32_e64 v240, v225, v224, s[46:47]
	v_cndmask_b32_e64 v241, v227, v226, s[46:47]
	v_cndmask_b32_e64 v242, v229, v228, s[46:47]
	v_cndmask_b32_e64 v243, v231, v230, s[46:47]
	s_waitcnt vmcnt(4)
	s_mov_b64 s[8:9], exec
	s_mov_b64 exec, s[52:53]
	v_pk_mul_f32 v[236:237], v[192:193], v[236:237]
	v_pk_mul_f32 v[238:239], v[194:195], v[238:239]
	v_pk_mul_f32 v[240:241], v[196:197], v[240:241]
	v_pk_mul_f32 v[242:243], v[198:199], v[242:243]
	v_pk_mul_f32 v[236:237], v[160:161], v[236:237]
	v_pk_mul_f32 v[238:239], v[160:161], v[238:239]
	v_pk_mul_f32 v[240:241], v[160:161], v[240:241]
	v_pk_mul_f32 v[242:243], v[160:161], v[242:243]
	v_pk_fma_f32 v[124:125], v[124:125], v[164:165], v[236:237]
	v_pk_fma_f32 v[126:127], v[126:127], v[166:167], v[238:239]
	v_pk_fma_f32 v[120:121], v[120:121], v[168:169], v[240:241]
	v_pk_fma_f32 v[122:123], v[122:123], v[170:171], v[242:243]
	s_mov_b64 exec, s[8:9]
	v_pk_mul_f32 v[124:125], v[162:163], v[124:125]
	v_pk_mul_f32 v[126:127], v[162:163], v[126:127]
	v_pk_mul_f32 v[120:121], v[162:163], v[120:121]
	v_pk_mul_f32 v[122:123], v[162:163], v[122:123]
	v_mov_b32_e32 v159, v155
	v_cvt_pk_bf16_f32 v124, v124, v125
	v_cvt_pk_bf16_f32 v125, v126, v127
	v_cvt_pk_bf16_f32 v126, v120, v121
	v_cvt_pk_bf16_f32 v127, v122, v123
	global_store_dwordx4 v159, v[124:127], s[20:21]
	v_pk_mul_f32 v[116:117], v[116:117], v[248:249] op_sel_hi:[1,0]
	v_pk_mul_f32 v[118:119], v[118:119], v[248:249] op_sel_hi:[1,0]
	v_pk_mul_f32 v[112:113], v[112:113], v[248:249] op_sel_hi:[1,0]
	v_pk_mul_f32 v[114:115], v[114:115], v[248:249] op_sel_hi:[1,0]
	v_mov_b32_e32 v216, v116
	v_mov_b32_e32 v217, v116
	v_mov_b32_e32 v218, v117
	v_mov_b32_e32 v219, v117
	v_mov_b32_e32 v220, v118
	v_mov_b32_e32 v221, v118
	v_mov_b32_e32 v222, v119
	v_mov_b32_e32 v223, v119
	v_mov_b32_e32 v224, v112
	v_mov_b32_e32 v225, v112
	v_mov_b32_e32 v226, v113
	v_mov_b32_e32 v227, v113
	v_mov_b32_e32 v228, v114
	v_mov_b32_e32 v229, v114
	v_mov_b32_e32 v230, v115
	v_mov_b32_e32 v231, v115
	v_permlane16_swap_b32_e32 v216, v217
	v_permlane16_swap_b32_e32 v218, v219
	v_permlane16_swap_b32_e32 v220, v221
	v_permlane16_swap_b32_e32 v222, v223
	v_permlane16_swap_b32_e32 v224, v225
	v_permlane16_swap_b32_e32 v226, v227
	v_permlane16_swap_b32_e32 v228, v229
	v_permlane16_swap_b32_e32 v230, v231
	v_cndmask_b32_e64 v236, v217, v216, s[46:47]
	v_cndmask_b32_e64 v237, v219, v218, s[46:47]
	v_cndmask_b32_e64 v238, v221, v220, s[46:47]
	v_cndmask_b32_e64 v239, v223, v222, s[46:47]
	v_cndmask_b32_e64 v240, v225, v224, s[46:47]
	v_cndmask_b32_e64 v241, v227, v226, s[46:47]
	v_cndmask_b32_e64 v242, v229, v228, s[46:47]
	v_cndmask_b32_e64 v243, v231, v230, s[46:47]
	s_mov_b64 s[8:9], exec
	s_mov_b64 exec, s[52:53]
	v_pk_mul_f32 v[236:237], v[192:193], v[236:237]
	v_pk_mul_f32 v[238:239], v[194:195], v[238:239]
	v_pk_mul_f32 v[240:241], v[196:197], v[240:241]
	v_pk_mul_f32 v[242:243], v[198:199], v[242:243]
	v_pk_mul_f32 v[236:237], v[160:161], v[236:237]
	v_pk_mul_f32 v[238:239], v[160:161], v[238:239]
	v_pk_mul_f32 v[240:241], v[160:161], v[240:241]
	v_pk_mul_f32 v[242:243], v[160:161], v[242:243]
	v_pk_fma_f32 v[116:117], v[116:117], v[164:165], v[236:237]
	v_pk_fma_f32 v[118:119], v[118:119], v[166:167], v[238:239]
	v_pk_fma_f32 v[112:113], v[112:113], v[168:169], v[240:241]
	v_pk_fma_f32 v[114:115], v[114:115], v[170:171], v[242:243]
	s_mov_b64 exec, s[8:9]
	v_pk_mul_f32 v[116:117], v[162:163], v[116:117]
	v_pk_mul_f32 v[118:119], v[162:163], v[118:119]
	v_pk_mul_f32 v[112:113], v[162:163], v[112:113]
	v_pk_mul_f32 v[114:115], v[162:163], v[114:115]
	v_mov_b32_e32 v159, v156
	v_cvt_pk_bf16_f32 v116, v116, v117
	v_cvt_pk_bf16_f32 v117, v118, v119
	v_cvt_pk_bf16_f32 v118, v112, v113
	v_cvt_pk_bf16_f32 v119, v114, v115
	global_store_dwordx4 v159, v[116:119], s[20:21]
	v_add_u32_e32 v158, 0x800, v157
	s_mov_b64 s[8:9], exec
	s_mov_b64 exec, s[52:53]
	global_load_dwordx4 v[164:167], v158, s[14:15] offset:0
	global_load_dwordx4 v[168:171], v158, s[14:15] offset:16
	global_load_dwordx4 v[192:195], v158, s[14:15] offset:32
	global_load_dwordx4 v[196:199], v158, s[14:15] offset:48
	s_mov_b64 exec, s[8:9]
	v_pk_mul_f32 v[108:109], v[108:109], v[248:249] op_sel:[0,1] op_sel_hi:[1,1]
	v_pk_mul_f32 v[110:111], v[110:111], v[248:249] op_sel:[0,1] op_sel_hi:[1,1]
	v_pk_mul_f32 v[104:105], v[104:105], v[248:249] op_sel:[0,1] op_sel_hi:[1,1]
	v_pk_mul_f32 v[106:107], v[106:107], v[248:249] op_sel:[0,1] op_sel_hi:[1,1]
	v_mov_b32_e32 v216, v108
	v_mov_b32_e32 v217, v108
	v_mov_b32_e32 v218, v109
	v_mov_b32_e32 v219, v109
	v_mov_b32_e32 v220, v110
	v_mov_b32_e32 v221, v110
	v_mov_b32_e32 v222, v111
	v_mov_b32_e32 v223, v111
	v_mov_b32_e32 v224, v104
	v_mov_b32_e32 v225, v104
	v_mov_b32_e32 v226, v105
	v_mov_b32_e32 v227, v105
	v_mov_b32_e32 v228, v106
	v_mov_b32_e32 v229, v106
	v_mov_b32_e32 v230, v107
	v_mov_b32_e32 v231, v107
	v_permlane16_swap_b32_e32 v216, v217
	v_permlane16_swap_b32_e32 v218, v219
	v_permlane16_swap_b32_e32 v220, v221
	v_permlane16_swap_b32_e32 v222, v223
	v_permlane16_swap_b32_e32 v224, v225
	v_permlane16_swap_b32_e32 v226, v227
	v_permlane16_swap_b32_e32 v228, v229
	v_permlane16_swap_b32_e32 v230, v231
	v_cndmask_b32_e64 v236, v217, v216, s[46:47]
	v_cndmask_b32_e64 v237, v219, v218, s[46:47]
	v_cndmask_b32_e64 v238, v221, v220, s[46:47]
	v_cndmask_b32_e64 v239, v223, v222, s[46:47]
	v_cndmask_b32_e64 v240, v225, v224, s[46:47]
	v_cndmask_b32_e64 v241, v227, v226, s[46:47]
	v_cndmask_b32_e64 v242, v229, v228, s[46:47]
	v_cndmask_b32_e64 v243, v231, v230, s[46:47]
	s_waitcnt vmcnt(6)
	s_mov_b64 s[8:9], exec
	s_mov_b64 exec, s[52:53]
	v_pk_mul_f32 v[236:237], v[208:209], v[236:237]
	v_pk_mul_f32 v[238:239], v[210:211], v[238:239]
	v_pk_mul_f32 v[240:241], v[232:233], v[240:241]
	v_pk_mul_f32 v[242:243], v[234:235], v[242:243]
	v_pk_mul_f32 v[236:237], v[160:161], v[236:237]
	v_pk_mul_f32 v[238:239], v[160:161], v[238:239]
	v_pk_mul_f32 v[240:241], v[160:161], v[240:241]
	v_pk_mul_f32 v[242:243], v[160:161], v[242:243]
	v_pk_fma_f32 v[108:109], v[108:109], v[200:201], v[236:237]
	v_pk_fma_f32 v[110:111], v[110:111], v[202:203], v[238:239]
	v_pk_fma_f32 v[104:105], v[104:105], v[204:205], v[240:241]
	v_pk_fma_f32 v[106:107], v[106:107], v[206:207], v[242:243]
	s_mov_b64 exec, s[8:9]
	v_pk_mul_f32 v[108:109], v[162:163], v[108:109]
	v_pk_mul_f32 v[110:111], v[162:163], v[110:111]
	v_pk_mul_f32 v[104:105], v[162:163], v[104:105]
	v_pk_mul_f32 v[106:107], v[162:163], v[106:107]
	v_add_u32_e32 v159, 0x800, v155
	v_cvt_pk_bf16_f32 v108, v108, v109
	v_cvt_pk_bf16_f32 v109, v110, v111
	v_cvt_pk_bf16_f32 v110, v104, v105
	v_cvt_pk_bf16_f32 v111, v106, v107
	global_store_dwordx4 v159, v[108:111], s[20:21]
	v_pk_mul_f32 v[100:101], v[100:101], v[248:249] op_sel:[0,1] op_sel_hi:[1,1]
	v_pk_mul_f32 v[102:103], v[102:103], v[248:249] op_sel:[0,1] op_sel_hi:[1,1]
	v_pk_mul_f32 v[96:97], v[96:97], v[248:249] op_sel:[0,1] op_sel_hi:[1,1]
	v_pk_mul_f32 v[98:99], v[98:99], v[248:249] op_sel:[0,1] op_sel_hi:[1,1]
	v_mov_b32_e32 v216, v100
	v_mov_b32_e32 v217, v100
	v_mov_b32_e32 v218, v101
	v_mov_b32_e32 v219, v101
	v_mov_b32_e32 v220, v102
	v_mov_b32_e32 v221, v102
	v_mov_b32_e32 v222, v103
	v_mov_b32_e32 v223, v103
	v_mov_b32_e32 v224, v96
	v_mov_b32_e32 v225, v96
	v_mov_b32_e32 v226, v97
	v_mov_b32_e32 v227, v97
	v_mov_b32_e32 v228, v98
	v_mov_b32_e32 v229, v98
	v_mov_b32_e32 v230, v99
	v_mov_b32_e32 v231, v99
	v_permlane16_swap_b32_e32 v216, v217
	v_permlane16_swap_b32_e32 v218, v219
	v_permlane16_swap_b32_e32 v220, v221
	v_permlane16_swap_b32_e32 v222, v223
	v_permlane16_swap_b32_e32 v224, v225
	v_permlane16_swap_b32_e32 v226, v227
	v_permlane16_swap_b32_e32 v228, v229
	v_permlane16_swap_b32_e32 v230, v231
	v_cndmask_b32_e64 v236, v217, v216, s[46:47]
	v_cndmask_b32_e64 v237, v219, v218, s[46:47]
	v_cndmask_b32_e64 v238, v221, v220, s[46:47]
	v_cndmask_b32_e64 v239, v223, v222, s[46:47]
	v_cndmask_b32_e64 v240, v225, v224, s[46:47]
	v_cndmask_b32_e64 v241, v227, v226, s[46:47]
	v_cndmask_b32_e64 v242, v229, v228, s[46:47]
	v_cndmask_b32_e64 v243, v231, v230, s[46:47]
	s_mov_b64 s[8:9], exec
	s_mov_b64 exec, s[52:53]
	v_pk_mul_f32 v[236:237], v[208:209], v[236:237]
	v_pk_mul_f32 v[238:239], v[210:211], v[238:239]
	v_pk_mul_f32 v[240:241], v[232:233], v[240:241]
	v_pk_mul_f32 v[242:243], v[234:235], v[242:243]
	v_pk_mul_f32 v[236:237], v[160:161], v[236:237]
	v_pk_mul_f32 v[238:239], v[160:161], v[238:239]
	v_pk_mul_f32 v[240:241], v[160:161], v[240:241]
	v_pk_mul_f32 v[242:243], v[160:161], v[242:243]
	v_pk_fma_f32 v[100:101], v[100:101], v[200:201], v[236:237]
	v_pk_fma_f32 v[102:103], v[102:103], v[202:203], v[238:239]
	v_pk_fma_f32 v[96:97], v[96:97], v[204:205], v[240:241]
	v_pk_fma_f32 v[98:99], v[98:99], v[206:207], v[242:243]
	s_mov_b64 exec, s[8:9]
	v_pk_mul_f32 v[100:101], v[162:163], v[100:101]
	v_pk_mul_f32 v[102:103], v[162:163], v[102:103]
	v_pk_mul_f32 v[96:97], v[162:163], v[96:97]
	v_pk_mul_f32 v[98:99], v[162:163], v[98:99]
	v_add_u32_e32 v159, 0x800, v156
	v_cvt_pk_bf16_f32 v100, v100, v101
	v_cvt_pk_bf16_f32 v101, v102, v103
	v_cvt_pk_bf16_f32 v102, v96, v97
	v_cvt_pk_bf16_f32 v103, v98, v99
	global_store_dwordx4 v159, v[100:103], s[20:21]
	v_add_u32_e32 v158, 0xc00, v157
	s_mov_b64 s[8:9], exec
	s_mov_b64 exec, s[52:53]
	global_load_dwordx4 v[200:203], v158, s[14:15] offset:0
	global_load_dwordx4 v[204:207], v158, s[14:15] offset:16
	global_load_dwordx4 v[208:211], v158, s[14:15] offset:32
	global_load_dwordx4 v[232:235], v158, s[14:15] offset:48
	s_mov_b64 exec, s[8:9]
	v_pk_mul_f32 v[92:93], v[92:93], v[250:251] op_sel_hi:[1,0]
	v_pk_mul_f32 v[94:95], v[94:95], v[250:251] op_sel_hi:[1,0]
	v_pk_mul_f32 v[88:89], v[88:89], v[250:251] op_sel_hi:[1,0]
	v_pk_mul_f32 v[90:91], v[90:91], v[250:251] op_sel_hi:[1,0]
	v_mov_b32_e32 v216, v92
	v_mov_b32_e32 v217, v92
	v_mov_b32_e32 v218, v93
	v_mov_b32_e32 v219, v93
	v_mov_b32_e32 v220, v94
	v_mov_b32_e32 v221, v94
	v_mov_b32_e32 v222, v95
	v_mov_b32_e32 v223, v95
	v_mov_b32_e32 v224, v88
	v_mov_b32_e32 v225, v88
	v_mov_b32_e32 v226, v89
	v_mov_b32_e32 v227, v89
	v_mov_b32_e32 v228, v90
	v_mov_b32_e32 v229, v90
	v_mov_b32_e32 v230, v91
	v_mov_b32_e32 v231, v91
	v_permlane16_swap_b32_e32 v216, v217
	v_permlane16_swap_b32_e32 v218, v219
	v_permlane16_swap_b32_e32 v220, v221
	v_permlane16_swap_b32_e32 v222, v223
	v_permlane16_swap_b32_e32 v224, v225
	v_permlane16_swap_b32_e32 v226, v227
	v_permlane16_swap_b32_e32 v228, v229
	v_permlane16_swap_b32_e32 v230, v231
	v_cndmask_b32_e64 v236, v217, v216, s[46:47]
	v_cndmask_b32_e64 v237, v219, v218, s[46:47]
	v_cndmask_b32_e64 v238, v221, v220, s[46:47]
	v_cndmask_b32_e64 v239, v223, v222, s[46:47]
	v_cndmask_b32_e64 v240, v225, v224, s[46:47]
	v_cndmask_b32_e64 v241, v227, v226, s[46:47]
	v_cndmask_b32_e64 v242, v229, v228, s[46:47]
	v_cndmask_b32_e64 v243, v231, v230, s[46:47]
	s_waitcnt vmcnt(6)
	s_mov_b64 s[8:9], exec
	s_mov_b64 exec, s[52:53]
	v_pk_mul_f32 v[236:237], v[192:193], v[236:237]
	v_pk_mul_f32 v[238:239], v[194:195], v[238:239]
	v_pk_mul_f32 v[240:241], v[196:197], v[240:241]
	v_pk_mul_f32 v[242:243], v[198:199], v[242:243]
	v_pk_mul_f32 v[236:237], v[160:161], v[236:237]
	v_pk_mul_f32 v[238:239], v[160:161], v[238:239]
	v_pk_mul_f32 v[240:241], v[160:161], v[240:241]
	v_pk_mul_f32 v[242:243], v[160:161], v[242:243]
	v_pk_fma_f32 v[92:93], v[92:93], v[164:165], v[236:237]
	v_pk_fma_f32 v[94:95], v[94:95], v[166:167], v[238:239]
	v_pk_fma_f32 v[88:89], v[88:89], v[168:169], v[240:241]
	v_pk_fma_f32 v[90:91], v[90:91], v[170:171], v[242:243]
	s_mov_b64 exec, s[8:9]
	v_pk_mul_f32 v[92:93], v[162:163], v[92:93]
	v_pk_mul_f32 v[94:95], v[162:163], v[94:95]
	v_pk_mul_f32 v[88:89], v[162:163], v[88:89]
	v_pk_mul_f32 v[90:91], v[162:163], v[90:91]
	v_add_u32_e32 v159, 0x1000, v155
	v_cvt_pk_bf16_f32 v92, v92, v93
	v_cvt_pk_bf16_f32 v93, v94, v95
	v_cvt_pk_bf16_f32 v94, v88, v89
	v_cvt_pk_bf16_f32 v95, v90, v91
	global_store_dwordx4 v159, v[92:95], s[20:21]
	v_pk_mul_f32 v[80:81], v[80:81], v[250:251] op_sel_hi:[1,0]
	v_pk_mul_f32 v[82:83], v[82:83], v[250:251] op_sel_hi:[1,0]
	v_pk_mul_f32 v[72:73], v[72:73], v[250:251] op_sel_hi:[1,0]
	v_pk_mul_f32 v[74:75], v[74:75], v[250:251] op_sel_hi:[1,0]
	v_mov_b32_e32 v216, v80
	v_mov_b32_e32 v217, v80
	v_mov_b32_e32 v218, v81
	v_mov_b32_e32 v219, v81
	v_mov_b32_e32 v220, v82
	v_mov_b32_e32 v221, v82
	v_mov_b32_e32 v222, v83
	v_mov_b32_e32 v223, v83
	v_mov_b32_e32 v224, v72
	v_mov_b32_e32 v225, v72
	v_mov_b32_e32 v226, v73
	v_mov_b32_e32 v227, v73
	v_mov_b32_e32 v228, v74
	v_mov_b32_e32 v229, v74
	v_mov_b32_e32 v230, v75
	v_mov_b32_e32 v231, v75
	v_permlane16_swap_b32_e32 v216, v217
	v_permlane16_swap_b32_e32 v218, v219
	v_permlane16_swap_b32_e32 v220, v221
	v_permlane16_swap_b32_e32 v222, v223
	v_permlane16_swap_b32_e32 v224, v225
	v_permlane16_swap_b32_e32 v226, v227
	v_permlane16_swap_b32_e32 v228, v229
	v_permlane16_swap_b32_e32 v230, v231
	v_cndmask_b32_e64 v236, v217, v216, s[46:47]
	v_cndmask_b32_e64 v237, v219, v218, s[46:47]
	v_cndmask_b32_e64 v238, v221, v220, s[46:47]
	v_cndmask_b32_e64 v239, v223, v222, s[46:47]
	v_cndmask_b32_e64 v240, v225, v224, s[46:47]
	v_cndmask_b32_e64 v241, v227, v226, s[46:47]
	v_cndmask_b32_e64 v242, v229, v228, s[46:47]
	v_cndmask_b32_e64 v243, v231, v230, s[46:47]
	s_mov_b64 s[8:9], exec
	s_mov_b64 exec, s[52:53]
	v_pk_mul_f32 v[236:237], v[192:193], v[236:237]
	v_pk_mul_f32 v[238:239], v[194:195], v[238:239]
	v_pk_mul_f32 v[240:241], v[196:197], v[240:241]
	v_pk_mul_f32 v[242:243], v[198:199], v[242:243]
	v_pk_mul_f32 v[236:237], v[160:161], v[236:237]
	v_pk_mul_f32 v[238:239], v[160:161], v[238:239]
	v_pk_mul_f32 v[240:241], v[160:161], v[240:241]
	v_pk_mul_f32 v[242:243], v[160:161], v[242:243]
	v_pk_fma_f32 v[80:81], v[80:81], v[164:165], v[236:237]
	v_pk_fma_f32 v[82:83], v[82:83], v[166:167], v[238:239]
	v_pk_fma_f32 v[72:73], v[72:73], v[168:169], v[240:241]
	v_pk_fma_f32 v[74:75], v[74:75], v[170:171], v[242:243]
	s_mov_b64 exec, s[8:9]
	v_pk_mul_f32 v[80:81], v[162:163], v[80:81]
	v_pk_mul_f32 v[82:83], v[162:163], v[82:83]
	v_pk_mul_f32 v[72:73], v[162:163], v[72:73]
	v_pk_mul_f32 v[74:75], v[162:163], v[74:75]
	v_add_u32_e32 v159, 0x1000, v156
	v_cvt_pk_bf16_f32 v80, v80, v81
	v_cvt_pk_bf16_f32 v81, v82, v83
	v_cvt_pk_bf16_f32 v82, v72, v73
	v_cvt_pk_bf16_f32 v83, v74, v75
	global_store_dwordx4 v159, v[80:83], s[20:21]
	v_add_u32_e32 v158, 0x2000, v157
	s_mov_b64 s[8:9], exec
	s_mov_b64 exec, s[52:53]
	global_load_dwordx4 v[164:167], v158, s[14:15] offset:0
	global_load_dwordx4 v[168:171], v158, s[14:15] offset:16
	global_load_dwordx4 v[192:195], v158, s[14:15] offset:32
	global_load_dwordx4 v[196:199], v158, s[14:15] offset:48
	s_mov_b64 exec, s[8:9]
	v_pk_mul_f32 v[84:85], v[84:85], v[250:251] op_sel:[0,1] op_sel_hi:[1,1]
	v_pk_mul_f32 v[86:87], v[86:87], v[250:251] op_sel:[0,1] op_sel_hi:[1,1]
	v_pk_mul_f32 v[76:77], v[76:77], v[250:251] op_sel:[0,1] op_sel_hi:[1,1]
	v_pk_mul_f32 v[78:79], v[78:79], v[250:251] op_sel:[0,1] op_sel_hi:[1,1]
	v_mov_b32_e32 v216, v84
	v_mov_b32_e32 v217, v84
	v_mov_b32_e32 v218, v85
	v_mov_b32_e32 v219, v85
	v_mov_b32_e32 v220, v86
	v_mov_b32_e32 v221, v86
	v_mov_b32_e32 v222, v87
	v_mov_b32_e32 v223, v87
	v_mov_b32_e32 v224, v76
	v_mov_b32_e32 v225, v76
	v_mov_b32_e32 v226, v77
	v_mov_b32_e32 v227, v77
	v_mov_b32_e32 v228, v78
	v_mov_b32_e32 v229, v78
	v_mov_b32_e32 v230, v79
	v_mov_b32_e32 v231, v79
	v_permlane16_swap_b32_e32 v216, v217
	v_permlane16_swap_b32_e32 v218, v219
	v_permlane16_swap_b32_e32 v220, v221
	v_permlane16_swap_b32_e32 v222, v223
	v_permlane16_swap_b32_e32 v224, v225
	v_permlane16_swap_b32_e32 v226, v227
	v_permlane16_swap_b32_e32 v228, v229
	v_permlane16_swap_b32_e32 v230, v231
	v_cndmask_b32_e64 v236, v217, v216, s[46:47]
	v_cndmask_b32_e64 v237, v219, v218, s[46:47]
	v_cndmask_b32_e64 v238, v221, v220, s[46:47]
	v_cndmask_b32_e64 v239, v223, v222, s[46:47]
	v_cndmask_b32_e64 v240, v225, v224, s[46:47]
	v_cndmask_b32_e64 v241, v227, v226, s[46:47]
	v_cndmask_b32_e64 v242, v229, v228, s[46:47]
	v_cndmask_b32_e64 v243, v231, v230, s[46:47]
	s_waitcnt vmcnt(6)
	s_mov_b64 s[8:9], exec
	s_mov_b64 exec, s[52:53]
	v_pk_mul_f32 v[236:237], v[208:209], v[236:237]
	v_pk_mul_f32 v[238:239], v[210:211], v[238:239]
	v_pk_mul_f32 v[240:241], v[232:233], v[240:241]
	v_pk_mul_f32 v[242:243], v[234:235], v[242:243]
	v_pk_mul_f32 v[236:237], v[160:161], v[236:237]
	v_pk_mul_f32 v[238:239], v[160:161], v[238:239]
	v_pk_mul_f32 v[240:241], v[160:161], v[240:241]
	v_pk_mul_f32 v[242:243], v[160:161], v[242:243]
	v_pk_fma_f32 v[84:85], v[84:85], v[200:201], v[236:237]
	v_pk_fma_f32 v[86:87], v[86:87], v[202:203], v[238:239]
	v_pk_fma_f32 v[76:77], v[76:77], v[204:205], v[240:241]
	v_pk_fma_f32 v[78:79], v[78:79], v[206:207], v[242:243]
	s_mov_b64 exec, s[8:9]
	v_pk_mul_f32 v[84:85], v[162:163], v[84:85]
	v_pk_mul_f32 v[86:87], v[162:163], v[86:87]
	v_pk_mul_f32 v[76:77], v[162:163], v[76:77]
	v_pk_mul_f32 v[78:79], v[162:163], v[78:79]
	v_add_u32_e32 v159, 0x1800, v155
	v_cvt_pk_bf16_f32 v84, v84, v85
	v_cvt_pk_bf16_f32 v85, v86, v87
	v_cvt_pk_bf16_f32 v86, v76, v77
	v_cvt_pk_bf16_f32 v87, v78, v79
	global_store_dwordx4 v159, v[84:87], s[20:21]
	v_pk_mul_f32 v[68:69], v[68:69], v[250:251] op_sel:[0,1] op_sel_hi:[1,1]
	v_pk_mul_f32 v[70:71], v[70:71], v[250:251] op_sel:[0,1] op_sel_hi:[1,1]
	v_pk_mul_f32 v[64:65], v[64:65], v[250:251] op_sel:[0,1] op_sel_hi:[1,1]
	v_pk_mul_f32 v[66:67], v[66:67], v[250:251] op_sel:[0,1] op_sel_hi:[1,1]
	v_mov_b32_e32 v216, v68
	v_mov_b32_e32 v217, v68
	v_mov_b32_e32 v218, v69
	v_mov_b32_e32 v219, v69
	v_mov_b32_e32 v220, v70
	v_mov_b32_e32 v221, v70
	v_mov_b32_e32 v222, v71
	v_mov_b32_e32 v223, v71
	v_mov_b32_e32 v224, v64
	v_mov_b32_e32 v225, v64
	v_mov_b32_e32 v226, v65
	v_mov_b32_e32 v227, v65
	v_mov_b32_e32 v228, v66
	v_mov_b32_e32 v229, v66
	v_mov_b32_e32 v230, v67
	v_mov_b32_e32 v231, v67
	v_permlane16_swap_b32_e32 v216, v217
	v_permlane16_swap_b32_e32 v218, v219
	v_permlane16_swap_b32_e32 v220, v221
	v_permlane16_swap_b32_e32 v222, v223
	v_permlane16_swap_b32_e32 v224, v225
	v_permlane16_swap_b32_e32 v226, v227
	v_permlane16_swap_b32_e32 v228, v229
	v_permlane16_swap_b32_e32 v230, v231
	v_cndmask_b32_e64 v236, v217, v216, s[46:47]
	v_cndmask_b32_e64 v237, v219, v218, s[46:47]
	v_cndmask_b32_e64 v238, v221, v220, s[46:47]
	v_cndmask_b32_e64 v239, v223, v222, s[46:47]
	v_cndmask_b32_e64 v240, v225, v224, s[46:47]
	v_cndmask_b32_e64 v241, v227, v226, s[46:47]
	v_cndmask_b32_e64 v242, v229, v228, s[46:47]
	v_cndmask_b32_e64 v243, v231, v230, s[46:47]
	s_mov_b64 s[8:9], exec
	s_mov_b64 exec, s[52:53]
	v_pk_mul_f32 v[236:237], v[208:209], v[236:237]
	v_pk_mul_f32 v[238:239], v[210:211], v[238:239]
	v_pk_mul_f32 v[240:241], v[232:233], v[240:241]
	v_pk_mul_f32 v[242:243], v[234:235], v[242:243]
	v_pk_mul_f32 v[236:237], v[160:161], v[236:237]
	v_pk_mul_f32 v[238:239], v[160:161], v[238:239]
	v_pk_mul_f32 v[240:241], v[160:161], v[240:241]
	v_pk_mul_f32 v[242:243], v[160:161], v[242:243]
	v_pk_fma_f32 v[68:69], v[68:69], v[200:201], v[236:237]
	v_pk_fma_f32 v[70:71], v[70:71], v[202:203], v[238:239]
	v_pk_fma_f32 v[64:65], v[64:65], v[204:205], v[240:241]
	v_pk_fma_f32 v[66:67], v[66:67], v[206:207], v[242:243]
	s_mov_b64 exec, s[8:9]
	v_pk_mul_f32 v[68:69], v[162:163], v[68:69]
	v_pk_mul_f32 v[70:71], v[162:163], v[70:71]
	v_pk_mul_f32 v[64:65], v[162:163], v[64:65]
	v_pk_mul_f32 v[66:67], v[162:163], v[66:67]
	v_add_u32_e32 v159, 0x1800, v156
	v_cvt_pk_bf16_f32 v68, v68, v69
	v_cvt_pk_bf16_f32 v69, v70, v71
	v_cvt_pk_bf16_f32 v70, v64, v65
	v_cvt_pk_bf16_f32 v71, v66, v67
	global_store_dwordx4 v159, v[68:71], s[20:21]
	v_add_u32_e32 v158, 0x2400, v157
	s_mov_b64 s[8:9], exec
	s_mov_b64 exec, s[52:53]
	global_load_dwordx4 v[200:203], v158, s[14:15] offset:0
	global_load_dwordx4 v[204:207], v158, s[14:15] offset:16
	global_load_dwordx4 v[208:211], v158, s[14:15] offset:32
	global_load_dwordx4 v[232:235], v158, s[14:15] offset:48
	s_mov_b64 exec, s[8:9]
	v_pk_mul_f32 v[60:61], v[60:61], v[252:253] op_sel_hi:[1,0]
	v_pk_mul_f32 v[62:63], v[62:63], v[252:253] op_sel_hi:[1,0]
	v_pk_mul_f32 v[56:57], v[56:57], v[252:253] op_sel_hi:[1,0]
	v_pk_mul_f32 v[58:59], v[58:59], v[252:253] op_sel_hi:[1,0]
	v_mov_b32_e32 v216, v60
	v_mov_b32_e32 v217, v60
	v_mov_b32_e32 v218, v61
	v_mov_b32_e32 v219, v61
	v_mov_b32_e32 v220, v62
	v_mov_b32_e32 v221, v62
	v_mov_b32_e32 v222, v63
	v_mov_b32_e32 v223, v63
	v_mov_b32_e32 v224, v56
	v_mov_b32_e32 v225, v56
	v_mov_b32_e32 v226, v57
	v_mov_b32_e32 v227, v57
	v_mov_b32_e32 v228, v58
	v_mov_b32_e32 v229, v58
	v_mov_b32_e32 v230, v59
	v_mov_b32_e32 v231, v59
	v_permlane16_swap_b32_e32 v216, v217
	v_permlane16_swap_b32_e32 v218, v219
	v_permlane16_swap_b32_e32 v220, v221
	v_permlane16_swap_b32_e32 v222, v223
	v_permlane16_swap_b32_e32 v224, v225
	v_permlane16_swap_b32_e32 v226, v227
	v_permlane16_swap_b32_e32 v228, v229
	v_permlane16_swap_b32_e32 v230, v231
	v_cndmask_b32_e64 v236, v217, v216, s[46:47]
	v_cndmask_b32_e64 v237, v219, v218, s[46:47]
	v_cndmask_b32_e64 v238, v221, v220, s[46:47]
	v_cndmask_b32_e64 v239, v223, v222, s[46:47]
	v_cndmask_b32_e64 v240, v225, v224, s[46:47]
	v_cndmask_b32_e64 v241, v227, v226, s[46:47]
	v_cndmask_b32_e64 v242, v229, v228, s[46:47]
	v_cndmask_b32_e64 v243, v231, v230, s[46:47]
	s_waitcnt vmcnt(6)
	s_mov_b64 s[8:9], exec
	s_mov_b64 exec, s[52:53]
	v_pk_mul_f32 v[236:237], v[192:193], v[236:237]
	v_pk_mul_f32 v[238:239], v[194:195], v[238:239]
	v_pk_mul_f32 v[240:241], v[196:197], v[240:241]
	v_pk_mul_f32 v[242:243], v[198:199], v[242:243]
	v_pk_mul_f32 v[236:237], v[160:161], v[236:237]
	v_pk_mul_f32 v[238:239], v[160:161], v[238:239]
	v_pk_mul_f32 v[240:241], v[160:161], v[240:241]
	v_pk_mul_f32 v[242:243], v[160:161], v[242:243]
	v_pk_fma_f32 v[60:61], v[60:61], v[164:165], v[236:237]
	v_pk_fma_f32 v[62:63], v[62:63], v[166:167], v[238:239]
	v_pk_fma_f32 v[56:57], v[56:57], v[168:169], v[240:241]
	v_pk_fma_f32 v[58:59], v[58:59], v[170:171], v[242:243]
	s_mov_b64 exec, s[8:9]
	v_pk_mul_f32 v[60:61], v[162:163], v[60:61]
	v_pk_mul_f32 v[62:63], v[162:163], v[62:63]
	v_pk_mul_f32 v[56:57], v[162:163], v[56:57]
	v_pk_mul_f32 v[58:59], v[162:163], v[58:59]
	v_add_u32_e32 v159, 0x4000, v155
	v_cvt_pk_bf16_f32 v60, v60, v61
	v_cvt_pk_bf16_f32 v61, v62, v63
	v_cvt_pk_bf16_f32 v62, v56, v57
	v_cvt_pk_bf16_f32 v63, v58, v59
	global_store_dwordx4 v159, v[60:63], s[20:21]
	v_pk_mul_f32 v[52:53], v[52:53], v[252:253] op_sel_hi:[1,0]
	v_pk_mul_f32 v[54:55], v[54:55], v[252:253] op_sel_hi:[1,0]
	v_pk_mul_f32 v[48:49], v[48:49], v[252:253] op_sel_hi:[1,0]
	v_pk_mul_f32 v[50:51], v[50:51], v[252:253] op_sel_hi:[1,0]
	v_mov_b32_e32 v216, v52
	v_mov_b32_e32 v217, v52
	v_mov_b32_e32 v218, v53
	v_mov_b32_e32 v219, v53
	v_mov_b32_e32 v220, v54
	v_mov_b32_e32 v221, v54
	v_mov_b32_e32 v222, v55
	v_mov_b32_e32 v223, v55
	v_mov_b32_e32 v224, v48
	v_mov_b32_e32 v225, v48
	v_mov_b32_e32 v226, v49
	v_mov_b32_e32 v227, v49
	v_mov_b32_e32 v228, v50
	v_mov_b32_e32 v229, v50
	v_mov_b32_e32 v230, v51
	v_mov_b32_e32 v231, v51
	v_permlane16_swap_b32_e32 v216, v217
	v_permlane16_swap_b32_e32 v218, v219
	v_permlane16_swap_b32_e32 v220, v221
	v_permlane16_swap_b32_e32 v222, v223
	v_permlane16_swap_b32_e32 v224, v225
	v_permlane16_swap_b32_e32 v226, v227
	v_permlane16_swap_b32_e32 v228, v229
	v_permlane16_swap_b32_e32 v230, v231
	v_cndmask_b32_e64 v236, v217, v216, s[46:47]
	v_cndmask_b32_e64 v237, v219, v218, s[46:47]
	v_cndmask_b32_e64 v238, v221, v220, s[46:47]
	v_cndmask_b32_e64 v239, v223, v222, s[46:47]
	v_cndmask_b32_e64 v240, v225, v224, s[46:47]
	v_cndmask_b32_e64 v241, v227, v226, s[46:47]
	v_cndmask_b32_e64 v242, v229, v228, s[46:47]
	v_cndmask_b32_e64 v243, v231, v230, s[46:47]
	s_mov_b64 s[8:9], exec
	s_mov_b64 exec, s[52:53]
	v_pk_mul_f32 v[236:237], v[192:193], v[236:237]
	v_pk_mul_f32 v[238:239], v[194:195], v[238:239]
	v_pk_mul_f32 v[240:241], v[196:197], v[240:241]
	v_pk_mul_f32 v[242:243], v[198:199], v[242:243]
	v_pk_mul_f32 v[236:237], v[160:161], v[236:237]
	v_pk_mul_f32 v[238:239], v[160:161], v[238:239]
	v_pk_mul_f32 v[240:241], v[160:161], v[240:241]
	v_pk_mul_f32 v[242:243], v[160:161], v[242:243]
	v_pk_fma_f32 v[52:53], v[52:53], v[164:165], v[236:237]
	v_pk_fma_f32 v[54:55], v[54:55], v[166:167], v[238:239]
	v_pk_fma_f32 v[48:49], v[48:49], v[168:169], v[240:241]
	v_pk_fma_f32 v[50:51], v[50:51], v[170:171], v[242:243]
	s_mov_b64 exec, s[8:9]
	v_pk_mul_f32 v[52:53], v[162:163], v[52:53]
	v_pk_mul_f32 v[54:55], v[162:163], v[54:55]
	v_pk_mul_f32 v[48:49], v[162:163], v[48:49]
	v_pk_mul_f32 v[50:51], v[162:163], v[50:51]
	v_add_u32_e32 v159, 0x4000, v156
	v_cvt_pk_bf16_f32 v52, v52, v53
	v_cvt_pk_bf16_f32 v53, v54, v55
	v_cvt_pk_bf16_f32 v54, v48, v49
	v_cvt_pk_bf16_f32 v55, v50, v51
	global_store_dwordx4 v159, v[52:55], s[20:21]
	v_add_u32_e32 v158, 0x2800, v157
	s_mov_b64 s[8:9], exec
	s_mov_b64 exec, s[52:53]
	global_load_dwordx4 v[164:167], v158, s[14:15] offset:0
	global_load_dwordx4 v[168:171], v158, s[14:15] offset:16
	global_load_dwordx4 v[192:195], v158, s[14:15] offset:32
	global_load_dwordx4 v[196:199], v158, s[14:15] offset:48
	s_mov_b64 exec, s[8:9]
	v_pk_mul_f32 v[44:45], v[44:45], v[252:253] op_sel:[0,1] op_sel_hi:[1,1]
	v_pk_mul_f32 v[46:47], v[46:47], v[252:253] op_sel:[0,1] op_sel_hi:[1,1]
	v_pk_mul_f32 v[40:41], v[40:41], v[252:253] op_sel:[0,1] op_sel_hi:[1,1]
	v_pk_mul_f32 v[42:43], v[42:43], v[252:253] op_sel:[0,1] op_sel_hi:[1,1]
	v_mov_b32_e32 v216, v44
	v_mov_b32_e32 v217, v44
	v_mov_b32_e32 v218, v45
	v_mov_b32_e32 v219, v45
	v_mov_b32_e32 v220, v46
	v_mov_b32_e32 v221, v46
	v_mov_b32_e32 v222, v47
	v_mov_b32_e32 v223, v47
	v_mov_b32_e32 v224, v40
	v_mov_b32_e32 v225, v40
	v_mov_b32_e32 v226, v41
	v_mov_b32_e32 v227, v41
	v_mov_b32_e32 v228, v42
	v_mov_b32_e32 v229, v42
	v_mov_b32_e32 v230, v43
	v_mov_b32_e32 v231, v43
	v_permlane16_swap_b32_e32 v216, v217
	v_permlane16_swap_b32_e32 v218, v219
	v_permlane16_swap_b32_e32 v220, v221
	v_permlane16_swap_b32_e32 v222, v223
	v_permlane16_swap_b32_e32 v224, v225
	v_permlane16_swap_b32_e32 v226, v227
	v_permlane16_swap_b32_e32 v228, v229
	v_permlane16_swap_b32_e32 v230, v231
	v_cndmask_b32_e64 v236, v217, v216, s[46:47]
	v_cndmask_b32_e64 v237, v219, v218, s[46:47]
	v_cndmask_b32_e64 v238, v221, v220, s[46:47]
	v_cndmask_b32_e64 v239, v223, v222, s[46:47]
	v_cndmask_b32_e64 v240, v225, v224, s[46:47]
	v_cndmask_b32_e64 v241, v227, v226, s[46:47]
	v_cndmask_b32_e64 v242, v229, v228, s[46:47]
	v_cndmask_b32_e64 v243, v231, v230, s[46:47]
	s_waitcnt vmcnt(6)
	s_mov_b64 s[8:9], exec
	s_mov_b64 exec, s[52:53]
	v_pk_mul_f32 v[236:237], v[208:209], v[236:237]
	v_pk_mul_f32 v[238:239], v[210:211], v[238:239]
	v_pk_mul_f32 v[240:241], v[232:233], v[240:241]
	v_pk_mul_f32 v[242:243], v[234:235], v[242:243]
	v_pk_mul_f32 v[236:237], v[160:161], v[236:237]
	v_pk_mul_f32 v[238:239], v[160:161], v[238:239]
	v_pk_mul_f32 v[240:241], v[160:161], v[240:241]
	v_pk_mul_f32 v[242:243], v[160:161], v[242:243]
	v_pk_fma_f32 v[44:45], v[44:45], v[200:201], v[236:237]
	v_pk_fma_f32 v[46:47], v[46:47], v[202:203], v[238:239]
	v_pk_fma_f32 v[40:41], v[40:41], v[204:205], v[240:241]
	v_pk_fma_f32 v[42:43], v[42:43], v[206:207], v[242:243]
	s_mov_b64 exec, s[8:9]
	v_pk_mul_f32 v[44:45], v[162:163], v[44:45]
	v_pk_mul_f32 v[46:47], v[162:163], v[46:47]
	v_pk_mul_f32 v[40:41], v[162:163], v[40:41]
	v_pk_mul_f32 v[42:43], v[162:163], v[42:43]
	v_add_u32_e32 v159, 0x4800, v155
	v_cvt_pk_bf16_f32 v44, v44, v45
	v_cvt_pk_bf16_f32 v45, v46, v47
	v_cvt_pk_bf16_f32 v46, v40, v41
	v_cvt_pk_bf16_f32 v47, v42, v43
	global_store_dwordx4 v159, v[44:47], s[20:21]
	v_pk_mul_f32 v[36:37], v[36:37], v[252:253] op_sel:[0,1] op_sel_hi:[1,1]
	v_pk_mul_f32 v[38:39], v[38:39], v[252:253] op_sel:[0,1] op_sel_hi:[1,1]
	v_pk_mul_f32 v[32:33], v[32:33], v[252:253] op_sel:[0,1] op_sel_hi:[1,1]
	v_pk_mul_f32 v[34:35], v[34:35], v[252:253] op_sel:[0,1] op_sel_hi:[1,1]
	v_mov_b32_e32 v216, v36
	v_mov_b32_e32 v217, v36
	v_mov_b32_e32 v218, v37
	v_mov_b32_e32 v219, v37
	v_mov_b32_e32 v220, v38
	v_mov_b32_e32 v221, v38
	v_mov_b32_e32 v222, v39
	v_mov_b32_e32 v223, v39
	v_mov_b32_e32 v224, v32
	v_mov_b32_e32 v225, v32
	v_mov_b32_e32 v226, v33
	v_mov_b32_e32 v227, v33
	v_mov_b32_e32 v228, v34
	v_mov_b32_e32 v229, v34
	v_mov_b32_e32 v230, v35
	v_mov_b32_e32 v231, v35
	v_permlane16_swap_b32_e32 v216, v217
	v_permlane16_swap_b32_e32 v218, v219
	v_permlane16_swap_b32_e32 v220, v221
	v_permlane16_swap_b32_e32 v222, v223
	v_permlane16_swap_b32_e32 v224, v225
	v_permlane16_swap_b32_e32 v226, v227
	v_permlane16_swap_b32_e32 v228, v229
	v_permlane16_swap_b32_e32 v230, v231
	v_cndmask_b32_e64 v236, v217, v216, s[46:47]
	v_cndmask_b32_e64 v237, v219, v218, s[46:47]
	v_cndmask_b32_e64 v238, v221, v220, s[46:47]
	v_cndmask_b32_e64 v239, v223, v222, s[46:47]
	v_cndmask_b32_e64 v240, v225, v224, s[46:47]
	v_cndmask_b32_e64 v241, v227, v226, s[46:47]
	v_cndmask_b32_e64 v242, v229, v228, s[46:47]
	v_cndmask_b32_e64 v243, v231, v230, s[46:47]
	s_mov_b64 s[8:9], exec
	s_mov_b64 exec, s[52:53]
	v_pk_mul_f32 v[236:237], v[208:209], v[236:237]
	v_pk_mul_f32 v[238:239], v[210:211], v[238:239]
	v_pk_mul_f32 v[240:241], v[232:233], v[240:241]
	v_pk_mul_f32 v[242:243], v[234:235], v[242:243]
	v_pk_mul_f32 v[236:237], v[160:161], v[236:237]
	v_pk_mul_f32 v[238:239], v[160:161], v[238:239]
	v_pk_mul_f32 v[240:241], v[160:161], v[240:241]
	v_pk_mul_f32 v[242:243], v[160:161], v[242:243]
	v_pk_fma_f32 v[36:37], v[36:37], v[200:201], v[236:237]
	v_pk_fma_f32 v[38:39], v[38:39], v[202:203], v[238:239]
	v_pk_fma_f32 v[32:33], v[32:33], v[204:205], v[240:241]
	v_pk_fma_f32 v[34:35], v[34:35], v[206:207], v[242:243]
	s_mov_b64 exec, s[8:9]
	v_pk_mul_f32 v[36:37], v[162:163], v[36:37]
	v_pk_mul_f32 v[38:39], v[162:163], v[38:39]
	v_pk_mul_f32 v[32:33], v[162:163], v[32:33]
	v_pk_mul_f32 v[34:35], v[162:163], v[34:35]
	v_add_u32_e32 v159, 0x4800, v156
	v_cvt_pk_bf16_f32 v36, v36, v37
	v_cvt_pk_bf16_f32 v37, v38, v39
	v_cvt_pk_bf16_f32 v38, v32, v33
	v_cvt_pk_bf16_f32 v39, v34, v35
	global_store_dwordx4 v159, v[36:39], s[20:21]
	v_add_u32_e32 v158, 0x2c00, v157
	s_mov_b64 s[8:9], exec
	s_mov_b64 exec, s[52:53]
	global_load_dwordx4 v[200:203], v158, s[14:15] offset:0
	global_load_dwordx4 v[204:207], v158, s[14:15] offset:16
	global_load_dwordx4 v[208:211], v158, s[14:15] offset:32
	global_load_dwordx4 v[232:235], v158, s[14:15] offset:48
	s_mov_b64 exec, s[8:9]
	v_pk_mul_f32 v[28:29], v[28:29], v[254:255] op_sel_hi:[1,0]
	v_pk_mul_f32 v[30:31], v[30:31], v[254:255] op_sel_hi:[1,0]
	v_pk_mul_f32 v[24:25], v[24:25], v[254:255] op_sel_hi:[1,0]
	v_pk_mul_f32 v[26:27], v[26:27], v[254:255] op_sel_hi:[1,0]
	v_mov_b32_e32 v216, v28
	v_mov_b32_e32 v217, v28
	v_mov_b32_e32 v218, v29
	v_mov_b32_e32 v219, v29
	v_mov_b32_e32 v220, v30
	v_mov_b32_e32 v221, v30
	v_mov_b32_e32 v222, v31
	v_mov_b32_e32 v223, v31
	v_mov_b32_e32 v224, v24
	v_mov_b32_e32 v225, v24
	v_mov_b32_e32 v226, v25
	v_mov_b32_e32 v227, v25
	v_mov_b32_e32 v228, v26
	v_mov_b32_e32 v229, v26
	v_mov_b32_e32 v230, v27
	v_mov_b32_e32 v231, v27
	v_permlane16_swap_b32_e32 v216, v217
	v_permlane16_swap_b32_e32 v218, v219
	v_permlane16_swap_b32_e32 v220, v221
	v_permlane16_swap_b32_e32 v222, v223
	v_permlane16_swap_b32_e32 v224, v225
	v_permlane16_swap_b32_e32 v226, v227
	v_permlane16_swap_b32_e32 v228, v229
	v_permlane16_swap_b32_e32 v230, v231
	v_cndmask_b32_e64 v236, v217, v216, s[46:47]
	v_cndmask_b32_e64 v237, v219, v218, s[46:47]
	v_cndmask_b32_e64 v238, v221, v220, s[46:47]
	v_cndmask_b32_e64 v239, v223, v222, s[46:47]
	v_cndmask_b32_e64 v240, v225, v224, s[46:47]
	v_cndmask_b32_e64 v241, v227, v226, s[46:47]
	v_cndmask_b32_e64 v242, v229, v228, s[46:47]
	v_cndmask_b32_e64 v243, v231, v230, s[46:47]
	s_waitcnt vmcnt(6)
	s_mov_b64 s[8:9], exec
	s_mov_b64 exec, s[52:53]
	v_pk_mul_f32 v[236:237], v[192:193], v[236:237]
	v_pk_mul_f32 v[238:239], v[194:195], v[238:239]
	v_pk_mul_f32 v[240:241], v[196:197], v[240:241]
	v_pk_mul_f32 v[242:243], v[198:199], v[242:243]
	v_pk_mul_f32 v[236:237], v[160:161], v[236:237]
	v_pk_mul_f32 v[238:239], v[160:161], v[238:239]
	v_pk_mul_f32 v[240:241], v[160:161], v[240:241]
	v_pk_mul_f32 v[242:243], v[160:161], v[242:243]
	v_pk_fma_f32 v[28:29], v[28:29], v[164:165], v[236:237]
	v_pk_fma_f32 v[30:31], v[30:31], v[166:167], v[238:239]
	v_pk_fma_f32 v[24:25], v[24:25], v[168:169], v[240:241]
	v_pk_fma_f32 v[26:27], v[26:27], v[170:171], v[242:243]
	s_mov_b64 exec, s[8:9]
	v_pk_mul_f32 v[28:29], v[162:163], v[28:29]
	v_pk_mul_f32 v[30:31], v[162:163], v[30:31]
	v_pk_mul_f32 v[24:25], v[162:163], v[24:25]
	v_pk_mul_f32 v[26:27], v[162:163], v[26:27]
	v_add_u32_e32 v159, 0x5000, v155
	v_cvt_pk_bf16_f32 v28, v28, v29
	v_cvt_pk_bf16_f32 v29, v30, v31
	v_cvt_pk_bf16_f32 v30, v24, v25
	v_cvt_pk_bf16_f32 v31, v26, v27
	global_store_dwordx4 v159, v[28:31], s[20:21]
	v_pk_mul_f32 v[20:21], v[20:21], v[254:255] op_sel_hi:[1,0]
	v_pk_mul_f32 v[22:23], v[22:23], v[254:255] op_sel_hi:[1,0]
	v_pk_mul_f32 v[16:17], v[16:17], v[254:255] op_sel_hi:[1,0]
	v_pk_mul_f32 v[18:19], v[18:19], v[254:255] op_sel_hi:[1,0]
	v_mov_b32_e32 v216, v20
	v_mov_b32_e32 v217, v20
	v_mov_b32_e32 v218, v21
	v_mov_b32_e32 v219, v21
	v_mov_b32_e32 v220, v22
	v_mov_b32_e32 v221, v22
	v_mov_b32_e32 v222, v23
	v_mov_b32_e32 v223, v23
	v_mov_b32_e32 v224, v16
	v_mov_b32_e32 v225, v16
	v_mov_b32_e32 v226, v17
	v_mov_b32_e32 v227, v17
	v_mov_b32_e32 v228, v18
	v_mov_b32_e32 v229, v18
	v_mov_b32_e32 v230, v19
	v_mov_b32_e32 v231, v19
	v_permlane16_swap_b32_e32 v216, v217
	v_permlane16_swap_b32_e32 v218, v219
	v_permlane16_swap_b32_e32 v220, v221
	v_permlane16_swap_b32_e32 v222, v223
	v_permlane16_swap_b32_e32 v224, v225
	v_permlane16_swap_b32_e32 v226, v227
	v_permlane16_swap_b32_e32 v228, v229
	v_permlane16_swap_b32_e32 v230, v231
	v_cndmask_b32_e64 v236, v217, v216, s[46:47]
	v_cndmask_b32_e64 v237, v219, v218, s[46:47]
	v_cndmask_b32_e64 v238, v221, v220, s[46:47]
	v_cndmask_b32_e64 v239, v223, v222, s[46:47]
	v_cndmask_b32_e64 v240, v225, v224, s[46:47]
	v_cndmask_b32_e64 v241, v227, v226, s[46:47]
	v_cndmask_b32_e64 v242, v229, v228, s[46:47]
	v_cndmask_b32_e64 v243, v231, v230, s[46:47]
	s_mov_b64 s[8:9], exec
	s_mov_b64 exec, s[52:53]
	v_pk_mul_f32 v[236:237], v[192:193], v[236:237]
	v_pk_mul_f32 v[238:239], v[194:195], v[238:239]
	v_pk_mul_f32 v[240:241], v[196:197], v[240:241]
	v_pk_mul_f32 v[242:243], v[198:199], v[242:243]
	v_pk_mul_f32 v[236:237], v[160:161], v[236:237]
	v_pk_mul_f32 v[238:239], v[160:161], v[238:239]
	v_pk_mul_f32 v[240:241], v[160:161], v[240:241]
	v_pk_mul_f32 v[242:243], v[160:161], v[242:243]
	v_pk_fma_f32 v[20:21], v[20:21], v[164:165], v[236:237]
	v_pk_fma_f32 v[22:23], v[22:23], v[166:167], v[238:239]
	v_pk_fma_f32 v[16:17], v[16:17], v[168:169], v[240:241]
	v_pk_fma_f32 v[18:19], v[18:19], v[170:171], v[242:243]
	s_mov_b64 exec, s[8:9]
	v_pk_mul_f32 v[20:21], v[162:163], v[20:21]
	v_pk_mul_f32 v[22:23], v[162:163], v[22:23]
	v_pk_mul_f32 v[16:17], v[162:163], v[16:17]
	v_pk_mul_f32 v[18:19], v[162:163], v[18:19]
	v_add_u32_e32 v159, 0x5000, v156
	v_cvt_pk_bf16_f32 v20, v20, v21
	v_cvt_pk_bf16_f32 v21, v22, v23
	v_cvt_pk_bf16_f32 v22, v16, v17
	v_cvt_pk_bf16_f32 v23, v18, v19
	global_store_dwordx4 v159, v[20:23], s[20:21]
	v_pk_mul_f32 v[12:13], v[12:13], v[254:255] op_sel:[0,1] op_sel_hi:[1,1]
	v_pk_mul_f32 v[14:15], v[14:15], v[254:255] op_sel:[0,1] op_sel_hi:[1,1]
	v_pk_mul_f32 v[8:9], v[8:9], v[254:255] op_sel:[0,1] op_sel_hi:[1,1]
	v_pk_mul_f32 v[10:11], v[10:11], v[254:255] op_sel:[0,1] op_sel_hi:[1,1]
	v_mov_b32_e32 v216, v12
	v_mov_b32_e32 v217, v12
	v_mov_b32_e32 v218, v13
	v_mov_b32_e32 v219, v13
	v_mov_b32_e32 v220, v14
	v_mov_b32_e32 v221, v14
	v_mov_b32_e32 v222, v15
	v_mov_b32_e32 v223, v15
	v_mov_b32_e32 v224, v8
	v_mov_b32_e32 v225, v8
	v_mov_b32_e32 v226, v9
	v_mov_b32_e32 v227, v9
	v_mov_b32_e32 v228, v10
	v_mov_b32_e32 v229, v10
	v_mov_b32_e32 v230, v11
	v_mov_b32_e32 v231, v11
	v_permlane16_swap_b32_e32 v216, v217
	v_permlane16_swap_b32_e32 v218, v219
	v_permlane16_swap_b32_e32 v220, v221
	v_permlane16_swap_b32_e32 v222, v223
	v_permlane16_swap_b32_e32 v224, v225
	v_permlane16_swap_b32_e32 v226, v227
	v_permlane16_swap_b32_e32 v228, v229
	v_permlane16_swap_b32_e32 v230, v231
	v_cndmask_b32_e64 v236, v217, v216, s[46:47]
	v_cndmask_b32_e64 v237, v219, v218, s[46:47]
	v_cndmask_b32_e64 v238, v221, v220, s[46:47]
	v_cndmask_b32_e64 v239, v223, v222, s[46:47]
	v_cndmask_b32_e64 v240, v225, v224, s[46:47]
	v_cndmask_b32_e64 v241, v227, v226, s[46:47]
	v_cndmask_b32_e64 v242, v229, v228, s[46:47]
	v_cndmask_b32_e64 v243, v231, v230, s[46:47]
	s_waitcnt vmcnt(2)
	s_mov_b64 s[8:9], exec
	s_mov_b64 exec, s[52:53]
	v_pk_mul_f32 v[236:237], v[208:209], v[236:237]
	v_pk_mul_f32 v[238:239], v[210:211], v[238:239]
	v_pk_mul_f32 v[240:241], v[232:233], v[240:241]
	v_pk_mul_f32 v[242:243], v[234:235], v[242:243]
	v_pk_mul_f32 v[236:237], v[160:161], v[236:237]
	v_pk_mul_f32 v[238:239], v[160:161], v[238:239]
	v_pk_mul_f32 v[240:241], v[160:161], v[240:241]
	v_pk_mul_f32 v[242:243], v[160:161], v[242:243]
	v_pk_fma_f32 v[12:13], v[12:13], v[200:201], v[236:237]
	v_pk_fma_f32 v[14:15], v[14:15], v[202:203], v[238:239]
	v_pk_fma_f32 v[8:9], v[8:9], v[204:205], v[240:241]
	v_pk_fma_f32 v[10:11], v[10:11], v[206:207], v[242:243]
	s_mov_b64 exec, s[8:9]
	v_pk_mul_f32 v[12:13], v[162:163], v[12:13]
	v_pk_mul_f32 v[14:15], v[162:163], v[14:15]
	v_pk_mul_f32 v[8:9], v[162:163], v[8:9]
	v_pk_mul_f32 v[10:11], v[162:163], v[10:11]
	v_add_u32_e32 v159, 0x5800, v155
	v_cvt_pk_bf16_f32 v12, v12, v13
	v_cvt_pk_bf16_f32 v13, v14, v15
	v_cvt_pk_bf16_f32 v14, v8, v9
	v_cvt_pk_bf16_f32 v15, v10, v11
	global_store_dwordx4 v159, v[12:15], s[20:21]
	v_pk_mul_f32 v[4:5], v[4:5], v[254:255] op_sel:[0,1] op_sel_hi:[1,1]
	v_pk_mul_f32 v[6:7], v[6:7], v[254:255] op_sel:[0,1] op_sel_hi:[1,1]
	v_pk_mul_f32 v[0:1], v[0:1], v[254:255] op_sel:[0,1] op_sel_hi:[1,1]
	v_pk_mul_f32 v[2:3], v[2:3], v[254:255] op_sel:[0,1] op_sel_hi:[1,1]
	v_mov_b32_e32 v216, v4
	v_mov_b32_e32 v217, v4
	v_mov_b32_e32 v218, v5
	v_mov_b32_e32 v219, v5
	v_mov_b32_e32 v220, v6
	v_mov_b32_e32 v221, v6
	v_mov_b32_e32 v222, v7
	v_mov_b32_e32 v223, v7
	v_mov_b32_e32 v224, v0
	v_mov_b32_e32 v225, v0
	v_mov_b32_e32 v226, v1
	v_mov_b32_e32 v227, v1
	v_mov_b32_e32 v228, v2
	v_mov_b32_e32 v229, v2
	v_mov_b32_e32 v230, v3
	v_mov_b32_e32 v231, v3
	v_permlane16_swap_b32_e32 v216, v217
	v_permlane16_swap_b32_e32 v218, v219
	v_permlane16_swap_b32_e32 v220, v221
	v_permlane16_swap_b32_e32 v222, v223
	v_permlane16_swap_b32_e32 v224, v225
	v_permlane16_swap_b32_e32 v226, v227
	v_permlane16_swap_b32_e32 v228, v229
	v_permlane16_swap_b32_e32 v230, v231
	v_cndmask_b32_e64 v236, v217, v216, s[46:47]
	v_cndmask_b32_e64 v237, v219, v218, s[46:47]
	v_cndmask_b32_e64 v238, v221, v220, s[46:47]
	v_cndmask_b32_e64 v239, v223, v222, s[46:47]
	v_cndmask_b32_e64 v240, v225, v224, s[46:47]
	v_cndmask_b32_e64 v241, v227, v226, s[46:47]
	v_cndmask_b32_e64 v242, v229, v228, s[46:47]
	v_cndmask_b32_e64 v243, v231, v230, s[46:47]
	s_mov_b64 s[8:9], exec
	s_mov_b64 exec, s[52:53]
	v_pk_mul_f32 v[236:237], v[208:209], v[236:237]
	v_pk_mul_f32 v[238:239], v[210:211], v[238:239]
	v_pk_mul_f32 v[240:241], v[232:233], v[240:241]
	v_pk_mul_f32 v[242:243], v[234:235], v[242:243]
	v_pk_mul_f32 v[236:237], v[160:161], v[236:237]
	v_pk_mul_f32 v[238:239], v[160:161], v[238:239]
	v_pk_mul_f32 v[240:241], v[160:161], v[240:241]
	v_pk_mul_f32 v[242:243], v[160:161], v[242:243]
	v_pk_fma_f32 v[4:5], v[4:5], v[200:201], v[236:237]
	v_pk_fma_f32 v[6:7], v[6:7], v[202:203], v[238:239]
	v_pk_fma_f32 v[0:1], v[0:1], v[204:205], v[240:241]
	v_pk_fma_f32 v[2:3], v[2:3], v[206:207], v[242:243]
	s_mov_b64 exec, s[8:9]
	v_pk_mul_f32 v[4:5], v[162:163], v[4:5]
	v_pk_mul_f32 v[6:7], v[162:163], v[6:7]
	v_pk_mul_f32 v[0:1], v[162:163], v[0:1]
	v_pk_mul_f32 v[2:3], v[162:163], v[2:3]
	v_add_u32_e32 v159, 0x5800, v156
	v_cvt_pk_bf16_f32 v4, v4, v5
	v_cvt_pk_bf16_f32 v5, v6, v7
	v_cvt_pk_bf16_f32 v6, v0, v1
	v_cvt_pk_bf16_f32 v7, v2, v3
	global_store_dwordx4 v159, v[4:7], s[20:21]
	s_branch .Lp1_done

.LBB0_323:
	s_lshl_b32 s20, s28, 6
	s_cmpk_lt_i32 s28, 0x100
	s_cselect_b32 s6, s19, 0x7fffc000
	s_cselect_b32 s29, s24, 0x4000
	s_and_b32 s21, s6, s20
	s_sub_i32 s30, s20, s21
	s_and_saveexec_b64 s[6:7], s[0:1]
	s_cbranch_execz .LBB0_328
	s_add_i32 s31, s30, -8
	v_ashrrev_i32_e32 v128, 5, v55
	v_mad_u64_u32 v[38:39], s[34:35], v128, s16, v[54:55]
	v_add_u32_e32 v130, s31, v128
	v_mov_b32_e32 v131, v130
	v_cmp_gt_u32_e32 vcc, s29, v131
	v_add_u32_e32 v152, s21, v131
	v_ashrrev_i32_e32 v153, 31, v152
	v_lshlrev_b64 v[152:153], 9, v[152:153]
	v_lshl_add_u64 v[152:153], v[52:53], 0, v[152:153]
	s_and_saveexec_b64 s[12:13], vcc
	global_load_dwordx4 v[132:135], v[152:153], off
	s_or_b64 exec, exec, s[12:13]
	v_add_u32_e32 v131, 16, v130
	v_cmp_gt_u32_e32 vcc, s29, v131
	v_add_u32_e32 v152, s21, v131
	v_ashrrev_i32_e32 v153, 31, v152
	v_lshlrev_b64 v[152:153], 9, v[152:153]
	v_lshl_add_u64 v[152:153], v[52:53], 0, v[152:153]
	s_and_saveexec_b64 s[12:13], vcc
	global_load_dwordx4 v[136:139], v[152:153], off
	s_or_b64 exec, exec, s[12:13]
	v_add_u32_e32 v131, 32, v130
	v_cmp_gt_u32_e32 vcc, s29, v131
	v_add_u32_e32 v152, s21, v131
	v_ashrrev_i32_e32 v153, 31, v152
	v_lshlrev_b64 v[152:153], 9, v[152:153]
	v_lshl_add_u64 v[152:153], v[52:53], 0, v[152:153]
	s_and_saveexec_b64 s[12:13], vcc
	global_load_dwordx4 v[140:143], v[152:153], off
	s_or_b64 exec, exec, s[12:13]
	v_add_u32_e32 v131, 48, v130
	v_cmp_gt_u32_e32 vcc, s29, v131
	v_add_u32_e32 v152, s21, v131
	v_ashrrev_i32_e32 v153, 31, v152
	v_lshlrev_b64 v[152:153], 9, v[152:153]
	v_lshl_add_u64 v[152:153], v[52:53], 0, v[152:153]
	s_and_saveexec_b64 s[12:13], vcc
	global_load_dwordx4 v[144:147], v[152:153], off
	s_or_b64 exec, exec, s[12:13]
	v_add_u32_e32 v131, 64, v130
	v_cmp_gt_u32_e32 vcc, s29, v131
	v_add_u32_e32 v152, s21, v131
	v_ashrrev_i32_e32 v153, 31, v152
	v_lshlrev_b64 v[152:153], 9, v[152:153]
	v_lshl_add_u64 v[152:153], v[52:53], 0, v[152:153]
	s_and_saveexec_b64 s[12:13], vcc
	global_load_dwordx4 v[148:151], v[152:153], off
	s_or_b64 exec, exec, s[12:13]
	s_waitcnt vmcnt(0)
	v_mov_b32_e32 v131, v130
	v_cmp_gt_u32_e32 vcc, s29, v131
	s_and_saveexec_b64 s[12:13], vcc
	ds_write_b128 v38, v[132:135] offset:0
	s_or_b64 exec, exec, s[12:13]
	v_add_u32_e32 v131, 16, v130
	v_cmp_gt_u32_e32 vcc, s29, v131
	s_and_saveexec_b64 s[12:13], vcc
	ds_write_b128 v38, v[136:139] offset:8448
	s_or_b64 exec, exec, s[12:13]
	v_add_u32_e32 v131, 32, v130
	v_cmp_gt_u32_e32 vcc, s29, v131
	s_and_saveexec_b64 s[12:13], vcc
	ds_write_b128 v38, v[140:143] offset:16896
	s_or_b64 exec, exec, s[12:13]
	v_add_u32_e32 v131, 48, v130
	v_cmp_gt_u32_e32 vcc, s29, v131
	s_and_saveexec_b64 s[12:13], vcc
	ds_write_b128 v38, v[144:147] offset:25344
	s_or_b64 exec, exec, s[12:13]
	v_add_u32_e32 v131, 64, v130
	v_cmp_gt_u32_e32 vcc, s29, v131
	s_and_saveexec_b64 s[12:13], vcc
	ds_write_b128 v38, v[148:151] offset:33792
	s_or_b64 exec, exec, s[12:13]
